# v24 plus counted lgkmcnt waits in the PV phase (each MFMA waits only for the transpose-reads it consumes)
# speedup vs baseline: 1.0107x; 1.0107x over previous
; #define SBAR() __builtin_amdgcn_sched_barrier(0)
; __device__ __forceinline__ void qkt(f32x16& p0, f32x16& p1, const bf16_t* Ks, const bf16x8* qr, int r32, int hi) {
;   p0 = f32x16{}; p1 = f32x16{};
; #pragma unroll
;   for (int d0 = 0; d0 < 8; ++d0) { int cb = (d0 * 16 + hi * 8) * 2;
;     bf16x8 b0 = *reinterpret_cast<const bf16x8*>((const char*)Ks + KSWZ(r32, cb));
;     bf16x8 b1 = *reinterpret_cast<const bf16x8*>((const char*)Ks + KSWZ(32 + r32, cb));
;     p0 = __builtin_amdgcn_mfma_f32_32x32x16_bf16(b0, qr[d0], p0, 0, 0, 0);
;     p1 = __builtin_amdgcn_mfma_f32_32x32x16_bf16(b1, qr[d0], p1, 0, 0, 0); }
; __device__ __forceinline__ void attn_body(const bf16_t* __restrict__ Qb, const bf16_t* __restrict__ Kh, const bf16_t* __restrict__ Vh,
;                                           bf16_t* __restrict__ Ob, const bf16_t* __restrict__ AGb, int seq, char* lds) {
;     ...
;     SBAR(); qkt(pB0, pB1, (bf16_t*)((char*)K_lds + SHM_K), qr, r32, hi);
;     finishSM(pA0, pA1, alA, l_reg, pa0, pa1, pa2, pa3); SBAR();
.LBB0_199:
	ds_read_b128 v[64:67], v206 offset:49152
	ds_read_b128 v[68:71], v206 offset:57344
	ds_read_b128 v[216:219], v211 offset:49152
	ds_read_b128 v[220:223], v211 offset:57344
	v_add_f32_e32 v162, 0, v163
	v_add_f32_e32 v162, v177, v162
	s_waitcnt lgkmcnt(3)
	v_mfma_f32_32x32x16_bf16 v[80:95], v[64:67], v[118:121], 0
	v_add_f32_e32 v162, v164, v162
	v_add_f32_e32 v162, v186, v162
	v_add_f32_e32 v162, v176, v162
	v_add_f32_e32 v162, v187, v162
	v_add_f32_e32 v162, v165, v162
	v_add_f32_e32 v162, v175, v162
	v_add_f32_e32 v162, v166, v162
	s_waitcnt lgkmcnt(2)
	v_mfma_f32_32x32x16_bf16 v[64:79], v[68:71], v[118:121], 0
	v_add_f32_e32 v162, v173, v162
	v_add_f32_e32 v162, v167, v162
	v_add_f32_e32 v162, v174, v162
	v_exp_f32_e32 v160, v160
	v_add_f32_e32 v162, v168, v162
	v_exp_f32_e32 v161, v161
	v_add_f32_e32 v162, v171, v162
	s_waitcnt lgkmcnt(1)
	v_mfma_f32_32x32x16_bf16 v[80:95], v[216:219], v[114:117], v[80:95]
	v_exp_f32_e32 v158, v158
	v_add_f32_e32 v162, v169, v162
	v_exp_f32_e32 v159, v159
	v_add_f32_e32 v162, v172, v162
	v_exp_f32_e32 v154, v154
	v_add_f32_e32 v162, v160, v162
	v_exp_f32_e32 v155, v155
	s_waitcnt lgkmcnt(0)
	v_mfma_f32_32x32x16_bf16 v[64:79], v[220:223], v[114:117], v[64:79]
	ds_read_b128 v[216:219], v210 offset:49152
	ds_read_b128 v[220:223], v210 offset:57344
	v_add_f32_e32 v162, v161, v162
	v_exp_f32_e32 v150, v150
	v_add_f32_e32 v162, v158, v162
	v_exp_f32_e32 v151, v151
	v_add_f32_e32 v162, v159, v162
	v_exp_f32_e32 v148, v148
	s_waitcnt lgkmcnt(1)
	v_mfma_f32_32x32x16_bf16 v[80:95], v[216:219], v[126:129], v[80:95]
	v_add_f32_e32 v162, v154, v162
	v_exp_f32_e32 v149, v149
	v_add_f32_e32 v162, v155, v162
	v_exp_f32_e32 v156, v156
	v_add_f32_e32 v162, v150, v162
	v_exp_f32_e32 v157, v157
	v_add_f32_e32 v162, v151, v162
	s_waitcnt lgkmcnt(0)
	v_mfma_f32_32x32x16_bf16 v[64:79], v[220:223], v[126:129], v[64:79]
	ds_read_b128 v[216:219], v209 offset:49152
	ds_read_b128 v[220:223], v209 offset:57344
	v_exp_f32_e32 v152, v152
	v_add_f32_e32 v162, v148, v162
	v_exp_f32_e32 v153, v153
	v_add_f32_e32 v162, v149, v162
	v_exp_f32_e32 v146, v146
	v_add_f32_e32 v162, v156, v162
	s_waitcnt lgkmcnt(1)
	v_mfma_f32_32x32x16_bf16 v[80:95], v[216:219], v[122:125], v[80:95]
	v_exp_f32_e32 v147, v147
	v_add_f32_e32 v162, v157, v162
	v_add_f32_e32 v162, v152, v162
	v_add_f32_e32 v162, v153, v162
	v_add_f32_e32 v162, v146, v162
	v_add_f32_e32 v215, v147, v162
	s_waitcnt lgkmcnt(0)
	v_mfma_f32_32x32x16_bf16 v[64:79], v[220:223], v[122:125], v[64:79]
	ds_read_b128 v[216:219], v208 offset:49152
	ds_read_b128 v[220:223], v208 offset:57344
	s_waitcnt lgkmcnt(1)
	v_mfma_f32_32x32x16_bf16 v[80:95], v[216:219], v[110:113], v[80:95]
	s_waitcnt lgkmcnt(0)
	v_mfma_f32_32x32x16_bf16 v[64:79], v[220:223], v[110:113], v[64:79]
	ds_read_b128 v[216:219], v207 offset:49152
	ds_read_b128 v[220:223], v207 offset:57344
	s_waitcnt lgkmcnt(1)
	v_mfma_f32_32x32x16_bf16 v[80:95], v[216:219], v[106:109], v[80:95]
	s_waitcnt lgkmcnt(0)
	v_mfma_f32_32x32x16_bf16 v[64:79], v[220:223], v[106:109], v[64:79]
	ds_read_b128 v[216:219], v213 offset:49152
	ds_read_b128 v[220:223], v213 offset:57344
	s_waitcnt lgkmcnt(1)
	v_mfma_f32_32x32x16_bf16 v[80:95], v[216:219], v[102:105], v[80:95]
	s_waitcnt lgkmcnt(0)
	v_mfma_f32_32x32x16_bf16 v[64:79], v[220:223], v[102:105], v[64:79]
	ds_read_b128 v[216:219], v212 offset:49152
	ds_read_b128 v[220:223], v212 offset:57344
	v_cvt_pk_bf16_f32 v162, v163, v177
	v_cvt_pk_bf16_f32 v163, v164, v186
	v_cvt_pk_bf16_f32 v164, v176, v187
	v_cvt_pk_bf16_f32 v165, v165, v175
	v_cvt_pk_bf16_f32 v166, v166, v173
	v_cvt_pk_bf16_f32 v167, v167, v174
	s_waitcnt lgkmcnt(1)
	v_mfma_f32_32x32x16_bf16 v[80:95], v[216:219], v[98:101], v[80:95]
	v_mov_b32_e32 v216, v215
	s_nop 1
	v_permlane32_swap_b32_e32 v215, v216
	v_permlane32_swap_b32_e32 v162, v164
	v_cvt_pk_bf16_f32 v168, v168, v171
	v_cvt_pk_bf16_f32 v169, v169, v172
	s_waitcnt lgkmcnt(0)
	v_mfma_f32_32x32x16_bf16 v[64:79], v[220:223], v[98:101], v[64:79]
	ds_read_b64_tr_b16 v[222:223], v201 offset:0
	ds_read_b64_tr_b16 v[224:225], v201 offset:0x800
	ds_read_b64_tr_b16 v[226:227], v201 offset:0x1000
	ds_read_b64_tr_b16 v[228:229], v201 offset:0x1800
	ds_read_b64_tr_b16 v[230:231], v201 offset:0x2000
	ds_read_b64_tr_b16 v[232:233], v201 offset:0x2800
	ds_read_b64_tr_b16 v[234:235], v201 offset:0x3000
	ds_read_b64_tr_b16 v[236:237], v201 offset:0x3800
	v_cvt_pk_bf16_f32 v172, v160, v161
	v_cvt_pk_bf16_f32 v173, v158, v159
	v_cvt_pk_bf16_f32 v174, v154, v155
	v_cvt_pk_bf16_f32 v175, v150, v151
	v_cvt_pk_bf16_f32 v218, v148, v149
	v_cvt_pk_bf16_f32 v219, v156, v157
	v_cvt_pk_bf16_f32 v220, v152, v153
	v_cvt_pk_bf16_f32 v221, v146, v147
	v_permlane32_swap_b32_e32 v163, v165
	v_permlane32_swap_b32_e32 v166, v168
	v_permlane32_swap_b32_e32 v167, v169
	v_permlane32_swap_b32_e32 v172, v174
	v_permlane32_swap_b32_e32 v173, v175
	v_permlane32_swap_b32_e32 v218, v220
	v_permlane32_swap_b32_e32 v219, v221
	v_lshl_add_u64 v[188:189], s[20:21], 0, v[96:97]
	v_add_co_u32_e32 v146, vcc, s63, v188
	v_lshl_add_u64 v[186:187], s[20:21], 0, v[184:185]
	s_nop 0
	v_addc_co_u32_e32 v147, vcc, 0, v189, vcc
	v_add_co_u32_e32 v150, vcc, s63, v186
	s_nop 1
	v_addc_co_u32_e32 v151, vcc, 0, v187, vcc
	v_add_co_u32_e32 v154, vcc, s90, v188
	global_load_dwordx4 v[146:149], v[146:147], off
	s_nop 0
	global_load_dwordx4 v[150:153], v[150:151], off
	v_addc_co_u32_e32 v155, vcc, 0, v189, vcc
	v_add_co_u32_e32 v158, vcc, s90, v186
	s_nop 1
	v_addc_co_u32_e32 v159, vcc, 0, v187, vcc
	global_load_dwordx4 v[154:157], v[154:155], off
	s_nop 0
	global_load_dwordx4 v[158:161], v[158:159], off
	s_waitcnt lgkmcnt(0)
; #define SBAR() __builtin_amdgcn_sched_barrier(0)
; template <int D0> __device__ __forceinline__ void pv_one(f32x16& od, int vb, bf16x8 pa0, bf16x8 pa1, bf16x8 pa2, bf16x8 pa3) {
;   const s16x4 l0 = tr_read<v_rd_off(D0, 0, 0)>(vb), h0 = tr_read<v_rd_off(D0, 0, 1)>(vb), l1 = tr_read<v_rd_off(D0, 1, 0)>(vb), h1 = tr_read<v_rd_off(D0, 1, 1)>(vb);
;   const s16x4 l2 = tr_read<v_rd_off(D0, 2, 0)>(vb), h2 = tr_read<v_rd_off(D0, 2, 1)>(vb), l3 = tr_read<v_rd_off(D0, 3, 0)>(vb), h3 = tr_read<v_rd_off(D0, 3, 1)>(vb);
;   asm volatile("s_waitcnt lgkmcnt(0)" ::: "memory"); SBAR();
;     ...
;   od = __builtin_amdgcn_mfma_f32_32x32x16_bf16(pa0, PK(l0, h0), od, 0, 0, 0);
;   od = __builtin_amdgcn_mfma_f32_32x32x16_bf16(pa1, PK(l1, h1), od, 0, 0, 0);
;   od = __builtin_amdgcn_mfma_f32_32x32x16_bf16(pa2, PK(l2, h2), od, 0, 0, 0);
;   od = __builtin_amdgcn_mfma_f32_32x32x16_bf16(pa3, PK(l3, h3), od, 0, 0, 0);
;     ...
; }
; __device__ __forceinline__ void pv_d0(f32x16* o, int vb, bf16x8 pa0, bf16x8 pa1, bf16x8 pa2, bf16x8 pa3) {
;   pv_one<0>(o[0], vb, pa0, pa1, pa2, pa3); pv_one<1>(o[1], vb, pa0, pa1, pa2, pa3); pv_one<2>(o[2], vb, pa0, pa1, pa2, pa3); pv_one<3>(o[3], vb, pa0, pa1, pa2, pa3);
; }
; __device__ __forceinline__ void attn_body(const bf16_t* __restrict__ Qb, const bf16_t* __restrict__ Kh, const bf16_t* __restrict__ Vh,
;                                           bf16_t* __restrict__ Ob, const bf16_t* __restrict__ AGb, int seq, char* lds) {
;     ...
;     pv_d0(o, vb0, pa0, pa1, pa2, pa3); partialSM(pB0, pB1, m_reg, mnB, alB);
	s_nop 0
	v_mfma_f32_32x32x16_bf16 v[0:15], v[162:165], v[222:225], v[0:15]
	ds_read_b64_tr_b16 v[222:223], v201 offset:0x200
	ds_read_b64_tr_b16 v[224:225], v201 offset:0xa00
	v_mfma_f32_32x32x16_bf16 v[0:15], v[166:169], v[226:229], v[0:15]
	ds_read_b64_tr_b16 v[226:227], v201 offset:0x1200
	ds_read_b64_tr_b16 v[228:229], v201 offset:0x1a00
	v_mfma_f32_32x32x16_bf16 v[0:15], v[172:175], v[230:233], v[0:15]
	ds_read_b64_tr_b16 v[230:231], v201 offset:0x2200
	ds_read_b64_tr_b16 v[232:233], v201 offset:0x2a00
	v_mfma_f32_32x32x16_bf16 v[0:15], v[218:221], v[234:237], v[0:15]
	ds_read_b64_tr_b16 v[234:235], v201 offset:0x3200
	ds_read_b64_tr_b16 v[236:237], v201 offset:0x3a00
	s_waitcnt lgkmcnt(6)
	v_mfma_f32_32x32x16_bf16 v[48:63], v[162:165], v[222:225], v[48:63]
	ds_read_b64_tr_b16 v[222:223], v201 offset:0x400
	ds_read_b64_tr_b16 v[224:225], v201 offset:0xc00
	s_waitcnt lgkmcnt(6)
	v_mfma_f32_32x32x16_bf16 v[48:63], v[166:169], v[226:229], v[48:63]
	ds_read_b64_tr_b16 v[226:227], v201 offset:0x1400
	ds_read_b64_tr_b16 v[228:229], v201 offset:0x1c00
	s_waitcnt lgkmcnt(6)
	v_mfma_f32_32x32x16_bf16 v[48:63], v[172:175], v[230:233], v[48:63]
	ds_read_b64_tr_b16 v[230:231], v201 offset:0x2400
	ds_read_b64_tr_b16 v[232:233], v201 offset:0x2c00
	s_waitcnt lgkmcnt(6)
	v_mfma_f32_32x32x16_bf16 v[48:63], v[218:221], v[234:237], v[48:63]
	ds_read_b64_tr_b16 v[234:235], v201 offset:0x3400
	ds_read_b64_tr_b16 v[236:237], v201 offset:0x3c00
	s_waitcnt lgkmcnt(6)
	v_mfma_f32_32x32x16_bf16 v[32:47], v[162:165], v[222:225], v[32:47]
	ds_read_b64_tr_b16 v[222:223], v201 offset:0x600
	ds_read_b64_tr_b16 v[224:225], v201 offset:0xe00
	s_waitcnt lgkmcnt(6)
	v_mfma_f32_32x32x16_bf16 v[32:47], v[166:169], v[226:229], v[32:47]
	ds_read_b64_tr_b16 v[226:227], v201 offset:0x1600
	ds_read_b64_tr_b16 v[228:229], v201 offset:0x1e00
	s_waitcnt lgkmcnt(6)
	v_mfma_f32_32x32x16_bf16 v[32:47], v[172:175], v[230:233], v[32:47]
	ds_read_b64_tr_b16 v[230:231], v201 offset:0x2600
	ds_read_b64_tr_b16 v[232:233], v201 offset:0x2e00
	s_waitcnt lgkmcnt(6)
	v_mfma_f32_32x32x16_bf16 v[32:47], v[218:221], v[234:237], v[32:47]
	ds_read_b64_tr_b16 v[234:235], v201 offset:0x3600
	ds_read_b64_tr_b16 v[236:237], v201 offset:0x3e00
	s_waitcnt lgkmcnt(6)
	v_mfma_f32_32x32x16_bf16 v[16:31], v[162:165], v[222:225], v[16:31]
	v_max_f32_e32 v162, v81, v81
	v_max_f32_e32 v163, v80, v80
	v_max_f32_e32 v162, v163, v162
	v_max3_f32 v162, v162, v82, v83
	v_max3_f32 v162, v162, v84, v85
	v_max3_f32 v162, v162, v86, v87
	v_max3_f32 v162, v162, v88, v89
	v_max3_f32 v162, v162, v90, v91
	v_max3_f32 v162, v162, v92, v93
	s_waitcnt lgkmcnt(4)
	v_mfma_f32_32x32x16_bf16 v[16:31], v[166:169], v[226:229], v[16:31]
	v_max3_f32 v162, v162, v94, v95
	v_max3_f32 v162, v162, v64, v65
	v_max3_f32 v162, v162, v66, v67
	v_max3_f32 v162, v162, v68, v69
	v_max3_f32 v162, v162, v70, v71
	v_max3_f32 v162, v162, v72, v73
	v_max3_f32 v162, v162, v74, v75
	v_max3_f32 v162, v162, v76, v77
	s_waitcnt lgkmcnt(2)
	v_mfma_f32_32x32x16_bf16 v[16:31], v[172:175], v[230:233], v[16:31]
	v_max3_f32 v162, v162, v78, v79
	v_mov_b32_e32 v163, v162
	s_nop 1
	v_permlane32_swap_b32_e32 v162, v163
	v_max_f32_e32 v163, v163, v163
	v_max_f32_e32 v162, v162, v162
	v_max_f32_e32 v162, v162, v163
	v_sub_f32_e32 v163, v162, v170
	v_cmp_ge_f32_e32 vcc, s62, v163
	v_max_f32_e32 v163, v170, v170
	v_max_f32_e32 v162, v163, v162
	s_waitcnt lgkmcnt(0)
	v_mfma_f32_32x32x16_bf16 v[16:31], v[218:221], v[234:237], v[16:31]
	v_sub_f32_e32 v163, v170, v162
	v_mul_f32_e32 v163, 0x3e0293ee, v163
	v_exp_f32_e32 v163, v163
	s_cmp_eq_u64 vcc, exec
	s_cselect_b64 s[0:1], -1, 0
	s_waitcnt lgkmcnt(0)
	s_barrier
	s_waitcnt vmcnt(4)
	v_cndmask_b32_e64 v217, v163, 1.0, s[0:1]
	v_cmp_gt_f32_e32 vcc, 1.0, v217
	ds_write_b128 v204, v[130:133]
	ds_write_b128 v205, v[134:137]
	ds_write_b128 v202, v[138:141] offset:32768
	ds_write_b128 v203, v[142:145] offset:32768
	s_cbranch_vccz .LBB0_203
	s_and_saveexec_b64 s[22:23], s[4:5]
	ds_write_b32 v183, v217 offset:128
	s_or_b64 exec, exec, s[22:23]
	s_waitcnt lgkmcnt(0)
	v_add_u32_e32 v163, v181, v180
	ds_read_b128 v[164:167], v163 offset:224
	ds_read_b128 v[172:175], v163 offset:192
	ds_read_b128 v[218:221], v163 offset:160
	ds_read_b128 v[222:225], v163 offset:128
	s_waitcnt lgkmcnt(0)
	v_pk_mul_f32 v[12:13], v[12:13], v[164:165]
	v_pk_mul_f32 v[8:9], v[8:9], v[172:173]
	v_pk_mul_f32 v[4:5], v[4:5], v[218:219]
	v_pk_mul_f32 v[14:15], v[14:15], v[166:167]
	v_pk_mul_f32 v[10:11], v[10:11], v[174:175]
	v_pk_mul_f32 v[6:7], v[6:7], v[220:221]
	v_pk_mul_f32 v[2:3], v[2:3], v[224:225]
	v_pk_mul_f32 v[0:1], v[0:1], v[222:223]
	v_pk_mul_f32 v[60:61], v[60:61], v[164:165]
	v_pk_mul_f32 v[56:57], v[56:57], v[172:173]
	v_pk_mul_f32 v[52:53], v[52:53], v[218:219]
	v_pk_mul_f32 v[62:63], v[62:63], v[166:167]
	v_pk_mul_f32 v[58:59], v[58:59], v[174:175]
	v_pk_mul_f32 v[54:55], v[54:55], v[220:221]
	v_pk_mul_f32 v[50:51], v[50:51], v[224:225]
	v_pk_mul_f32 v[48:49], v[48:49], v[222:223]
	v_pk_mul_f32 v[44:45], v[44:45], v[164:165]
	v_pk_mul_f32 v[40:41], v[40:41], v[172:173]
	v_pk_mul_f32 v[36:37], v[36:37], v[218:219]
	v_pk_mul_f32 v[46:47], v[46:47], v[166:167]
	v_pk_mul_f32 v[42:43], v[42:43], v[174:175]
	v_pk_mul_f32 v[38:39], v[38:39], v[220:221]
	v_pk_mul_f32 v[34:35], v[34:35], v[224:225]
	v_pk_mul_f32 v[32:33], v[32:33], v[222:223]
	v_pk_mul_f32 v[28:29], v[28:29], v[164:165]
	v_pk_mul_f32 v[24:25], v[24:25], v[172:173]
	v_pk_mul_f32 v[20:21], v[20:21], v[218:219]
	v_pk_mul_f32 v[30:31], v[30:31], v[166:167]
	v_pk_mul_f32 v[26:27], v[26:27], v[174:175]
	v_pk_mul_f32 v[22:23], v[22:23], v[220:221]
	v_pk_mul_f32 v[18:19], v[18:19], v[224:225]
	v_pk_mul_f32 v[16:17], v[16:17], v[222:223]

; #define SBAR() __builtin_amdgcn_sched_barrier(0)
; #define SWRITE(b, i) do { *(bf16x8*)((char*)V_lds + (b) * SHM_V + vst0) = sr_[i].vs0;          \
;     *(bf16x8*)((char*)V_lds + (b) * SHM_V + vst1) = sr_[i].vs1; int kc = sc * 2;               \
;     *(bf16x8*)((char*)K_lds + (b) * SHM_K + KSWZ(sr, kc)) = sr_[i].ks0;                       \
;     *(bf16x8*)((char*)K_lds + (b) * SHM_K + KSWZ(32 + sr, kc)) = sr_[i].ks1; } while (0)
; #define SWAIT() asm volatile("s_waitcnt vmcnt(4)" ::: "memory")
; #define RESC(a) do { if (__any((a) < 1.f)) { if (hi == 0) al_l[r32] = (a); asm volatile("s_waitcnt lgkmcnt(0)" ::: "memory"); \
;     _Pragma("unroll") for (int d = 0; d < 4; ++d) _Pragma("unroll") for (int r = 0; r < 16; ++r) o[d][r] *= al_l[crow(r, hi)]; } } while (0)
; template <int D0> __device__ __forceinline__ void pv_one(f32x16& od, int vb, bf16x8 pa0, bf16x8 pa1, bf16x8 pa2, bf16x8 pa3) {
;   const s16x4 l0 = tr_read<v_rd_off(D0, 0, 0)>(vb), h0 = tr_read<v_rd_off(D0, 0, 1)>(vb), l1 = tr_read<v_rd_off(D0, 1, 0)>(vb), h1 = tr_read<v_rd_off(D0, 1, 1)>(vb);
;   const s16x4 l2 = tr_read<v_rd_off(D0, 2, 0)>(vb), h2 = tr_read<v_rd_off(D0, 2, 1)>(vb), l3 = tr_read<v_rd_off(D0, 3, 0)>(vb), h3 = tr_read<v_rd_off(D0, 3, 1)>(vb);
;   asm volatile("s_waitcnt lgkmcnt(0)" ::: "memory"); SBAR();
;     ...
;   od = __builtin_amdgcn_mfma_f32_32x32x16_bf16(pa0, PK(l0, h0), od, 0, 0, 0);
;   od = __builtin_amdgcn_mfma_f32_32x32x16_bf16(pa1, PK(l1, h1), od, 0, 0, 0);
;   od = __builtin_amdgcn_mfma_f32_32x32x16_bf16(pa2, PK(l2, h2), od, 0, 0, 0);
;   od = __builtin_amdgcn_mfma_f32_32x32x16_bf16(pa3, PK(l3, h3), od, 0, 0, 0);
;     ...
; }
; __device__ __forceinline__ void pv_d0(f32x16* o, int vb, bf16x8 pa0, bf16x8 pa1, bf16x8 pa2, bf16x8 pa3) {
;   pv_one<0>(o[0], vb, pa0, pa1, pa2, pa3); pv_one<1>(o[1], vb, pa0, pa1, pa2, pa3); pv_one<2>(o[2], vb, pa0, pa1, pa2, pa3); pv_one<3>(o[3], vb, pa0, pa1, pa2, pa3);
; }
; __device__ __forceinline__ void attn_body(const bf16_t* __restrict__ Qb, const bf16_t* __restrict__ Kh, const bf16_t* __restrict__ Vh,
;                                           bf16_t* __restrict__ Ob, const bf16_t* __restrict__ AGb, int seq, char* lds) {
;     ...
;     pv_d0(o, vb0 + (int)SHM_V, pa0, pa1, pa2, pa3); partialSM(pA0, pA1, m_reg, mnA, alA);
;     __syncthreads(); SWAIT(); SWRITE(1, SO);
;     RESC(alA); __syncthreads();
.LBB0_205:
	s_waitcnt lgkmcnt(0)
	s_nop 0
	v_mfma_f32_32x32x16_bf16 v[0:15], v[162:165], v[186:189], v[0:15]
	ds_read_b64_tr_b16 v[186:187], v200 offset:0x200
	ds_read_b64_tr_b16 v[188:189], v200 offset:0xa00
	v_mfma_f32_32x32x16_bf16 v[0:15], v[166:169], v[222:225], v[0:15]
	ds_read_b64_tr_b16 v[222:223], v200 offset:0x1200
	ds_read_b64_tr_b16 v[224:225], v200 offset:0x1a00
	v_mfma_f32_32x32x16_bf16 v[0:15], v[170:173], v[226:229], v[0:15]
	ds_read_b64_tr_b16 v[226:227], v200 offset:0x2200
	ds_read_b64_tr_b16 v[228:229], v200 offset:0x2a00
	v_mfma_f32_32x32x16_bf16 v[0:15], v[174:177], v[230:233], v[0:15]
	ds_read_b64_tr_b16 v[230:231], v200 offset:0x3200
	ds_read_b64_tr_b16 v[232:233], v200 offset:0x3a00
	s_waitcnt lgkmcnt(6)
	v_mfma_f32_32x32x16_bf16 v[48:63], v[162:165], v[186:189], v[48:63]
	ds_read_b64_tr_b16 v[186:187], v200 offset:0x400
	ds_read_b64_tr_b16 v[188:189], v200 offset:0xc00
	s_waitcnt lgkmcnt(6)
	v_mfma_f32_32x32x16_bf16 v[48:63], v[166:169], v[222:225], v[48:63]
	ds_read_b64_tr_b16 v[222:223], v200 offset:0x1400
	ds_read_b64_tr_b16 v[224:225], v200 offset:0x1c00
	s_waitcnt lgkmcnt(6)
	v_mfma_f32_32x32x16_bf16 v[48:63], v[170:173], v[226:229], v[48:63]
	ds_read_b64_tr_b16 v[226:227], v200 offset:0x2400
	ds_read_b64_tr_b16 v[228:229], v200 offset:0x2c00
	s_waitcnt lgkmcnt(6)
	v_mfma_f32_32x32x16_bf16 v[48:63], v[174:177], v[230:233], v[48:63]
	ds_read_b64_tr_b16 v[230:231], v200 offset:0x3400
	ds_read_b64_tr_b16 v[232:233], v200 offset:0x3c00
	s_waitcnt lgkmcnt(6)
	v_mfma_f32_32x32x16_bf16 v[32:47], v[162:165], v[186:189], v[32:47]
	ds_read_b64_tr_b16 v[186:187], v200 offset:0x600
	ds_read_b64_tr_b16 v[188:189], v200 offset:0xe00
	s_waitcnt lgkmcnt(6)
	v_mfma_f32_32x32x16_bf16 v[32:47], v[166:169], v[222:225], v[32:47]
	ds_read_b64_tr_b16 v[222:223], v200 offset:0x1600
	ds_read_b64_tr_b16 v[224:225], v200 offset:0x1e00
	s_waitcnt lgkmcnt(6)
	v_mfma_f32_32x32x16_bf16 v[32:47], v[170:173], v[226:229], v[32:47]
	ds_read_b64_tr_b16 v[226:227], v200 offset:0x2600
	ds_read_b64_tr_b16 v[228:229], v200 offset:0x2e00
	s_waitcnt lgkmcnt(6)
	v_mfma_f32_32x32x16_bf16 v[32:47], v[174:177], v[230:233], v[32:47]
	ds_read_b64_tr_b16 v[230:231], v200 offset:0x3600
	ds_read_b64_tr_b16 v[232:233], v200 offset:0x3e00
	s_waitcnt lgkmcnt(6)
	v_mfma_f32_32x32x16_bf16 v[16:31], v[162:165], v[186:189], v[16:31]
	v_max_f32_e32 v162, v81, v81
	v_max_f32_e32 v163, v80, v80
	v_max_f32_e32 v162, v163, v162
	v_max3_f32 v162, v162, v82, v83
	v_max3_f32 v162, v162, v84, v85
	v_max3_f32 v162, v162, v86, v87
	v_max3_f32 v162, v162, v88, v89
	v_max3_f32 v162, v162, v90, v91
	v_max3_f32 v162, v162, v92, v93
	s_waitcnt lgkmcnt(4)
	v_mfma_f32_32x32x16_bf16 v[16:31], v[166:169], v[222:225], v[16:31]
	v_max3_f32 v162, v162, v94, v95
	v_max3_f32 v162, v162, v64, v65
	v_max3_f32 v162, v162, v66, v67
	v_max3_f32 v162, v162, v68, v69
	v_max3_f32 v162, v162, v70, v71
	v_max3_f32 v162, v162, v72, v73
	v_max3_f32 v162, v162, v74, v75
	v_max3_f32 v162, v162, v76, v77
	s_waitcnt lgkmcnt(2)
	v_mfma_f32_32x32x16_bf16 v[16:31], v[170:173], v[226:229], v[16:31]
	v_max3_f32 v162, v162, v78, v79
	v_mov_b32_e32 v163, v162
	s_nop 1
	v_permlane32_swap_b32_e32 v162, v163
	v_max_f32_e32 v163, v163, v163
	v_max_f32_e32 v162, v162, v162
	v_max_f32_e32 v162, v162, v163
	v_sub_f32_e32 v163, v162, v218
	v_cmp_ge_f32_e32 vcc, s62, v163
	v_max_f32_e32 v163, v218, v218
	v_max_f32_e32 v163, v163, v162
	s_waitcnt lgkmcnt(0)
	v_mfma_f32_32x32x16_bf16 v[16:31], v[174:177], v[230:233], v[16:31]
	v_sub_f32_e32 v162, v218, v163
	v_mul_f32_e32 v162, 0x3e0293ee, v162
	v_exp_f32_e32 v162, v162
	s_cmp_eq_u64 vcc, exec
	s_cselect_b64 s[0:1], -1, 0
	s_waitcnt lgkmcnt(0)
	s_barrier
	s_waitcnt vmcnt(4)
	v_cndmask_b32_e64 v162, v162, 1.0, s[0:1]
	v_cmp_gt_f32_e32 vcc, 1.0, v162
	s_waitcnt vmcnt(0)
	ds_write_b128 v204, v[146:149] offset:16384
	ds_write_b128 v205, v[150:153] offset:16384
	ds_write_b128 v202, v[154:157] offset:49152
	ds_write_b128 v203, v[158:161] offset:49152
	s_cbranch_vccz .LBB0_209
	s_and_saveexec_b64 s[24:25], s[4:5]
	ds_write_b32 v183, v162 offset:128
	s_or_b64 exec, exec, s[24:25]
	s_waitcnt lgkmcnt(0)
	v_add_u32_e32 v158, v181, v180
	ds_read_b128 v[146:149], v158 offset:224
	ds_read_b128 v[150:153], v158 offset:192
	ds_read_b128 v[154:157], v158 offset:160
	ds_read_b128 v[158:161], v158 offset:128
	s_waitcnt lgkmcnt(3)
	v_pk_mul_f32 v[12:13], v[12:13], v[146:147]
	s_waitcnt lgkmcnt(2)
	v_pk_mul_f32 v[8:9], v[8:9], v[150:151]
	s_waitcnt lgkmcnt(1)
	v_pk_mul_f32 v[4:5], v[4:5], v[154:155]
	v_pk_mul_f32 v[14:15], v[14:15], v[148:149]
	v_pk_mul_f32 v[10:11], v[10:11], v[152:153]
	v_pk_mul_f32 v[6:7], v[6:7], v[156:157]
	s_waitcnt lgkmcnt(0)
	v_pk_mul_f32 v[2:3], v[2:3], v[160:161]
	v_pk_mul_f32 v[0:1], v[0:1], v[158:159]
	v_pk_mul_f32 v[60:61], v[60:61], v[146:147]
	v_pk_mul_f32 v[56:57], v[56:57], v[150:151]
	v_pk_mul_f32 v[52:53], v[52:53], v[154:155]
	v_pk_mul_f32 v[62:63], v[62:63], v[148:149]
	v_pk_mul_f32 v[58:59], v[58:59], v[152:153]
	v_pk_mul_f32 v[54:55], v[54:55], v[156:157]
	v_pk_mul_f32 v[50:51], v[50:51], v[160:161]
	v_pk_mul_f32 v[48:49], v[48:49], v[158:159]
	v_pk_mul_f32 v[44:45], v[44:45], v[146:147]
	v_pk_mul_f32 v[40:41], v[40:41], v[150:151]
	v_pk_mul_f32 v[36:37], v[36:37], v[154:155]
	v_pk_mul_f32 v[46:47], v[46:47], v[148:149]
	v_pk_mul_f32 v[42:43], v[42:43], v[152:153]
	v_pk_mul_f32 v[38:39], v[38:39], v[156:157]
	v_pk_mul_f32 v[34:35], v[34:35], v[160:161]
	v_pk_mul_f32 v[32:33], v[32:33], v[158:159]
	v_pk_mul_f32 v[28:29], v[28:29], v[146:147]
	v_pk_mul_f32 v[24:25], v[24:25], v[150:151]
	v_pk_mul_f32 v[20:21], v[20:21], v[154:155]
	v_pk_mul_f32 v[30:31], v[30:31], v[148:149]
	v_pk_mul_f32 v[26:27], v[26:27], v[152:153]
	v_pk_mul_f32 v[22:23], v[22:23], v[156:157]
	v_pk_mul_f32 v[18:19], v[18:19], v[160:161]
	v_pk_mul_f32 v[16:17], v[16:17], v[158:159]
